# attention unit epilogue: half-waves trade 8-byte pieces with v_permlane32_swap, 8 dwordx4 stores per lane instead of 16 dwordx2 (32 contiguous bytes per row per store)
# speedup vs baseline: 1.0009x; 1.0009x over previous
; __device__ __forceinline__ unsigned cvtpk(float lo, float hi) { f32x2 v = {lo, hi}; bf16x2_t b = __builtin_convertvector(v, bf16x2_t); return __builtin_bit_cast(unsigned, b); }
; __device__ __forceinline__ void attn_unit(LAS unsigned char* lds, int b, int hh, int qb, const bf16_t* QK, const bf16_t* VT, bf16_t* CAT) {
;     ...
;     lrun += __shfl_xor(lrun, 32);
;     const float inv = 1.0f / lrun;
;     bf16_t* Op = CAT + (size_t)(b * SEQ + qpos) * DM + hh * HD + 4 * hi;
; #pragma unroll
;     for (int d = 0; d < 4; ++d)
; #pragma unroll
;         for (int g = 0; g < 4; ++g) { u32x2 w; w.x = cvtpk(o[d][4 * g] * inv, o[d][4 * g + 1] * inv); w.y = cvtpk(o[d][4 * g + 2] * inv, o[d][4 * g + 3] * inv);
;             *(u32x2*)(Op + 32 * d + 8 * g) = w; }
.LBB0_226:
	ds_bpermute_b32 v68, v175, v187
	v_add_u32_e32 v66, s29, v146
	v_ashrrev_i32_e32 v67, 31, v66
	v_lshlrev_b64 v[66:67], 12, v[66:67]
	v_readlane_b32 s1, v248, 19
	s_waitcnt lgkmcnt(0)
	v_add_f32_e32 v68, v187, v68
	v_div_scale_f32 v69, s[2:3], v68, v68, 1.0
	v_rcp_f32_e32 v70, v69
	v_div_scale_f32 v71, vcc, 1.0, v68, 1.0
	v_readlane_b32 s2, v250, 53
	v_fma_f32 v72, -v69, v70, 1.0
	v_fmac_f32_e32 v70, v72, v70
	v_mul_f32_e32 v72, v71, v70
	v_fma_f32 v73, -v69, v72, v71
	v_fmac_f32_e32 v72, v73, v70
	v_fma_f32 v69, -v69, v72, v71
	v_div_fmas_f32 v69, v69, v70, v72
	v_readlane_b32 s3, v250, 54
	v_div_fixup_f32 v68, v69, v68, 1.0
	s_nop 1
	v_lshl_add_u64 v[66:67], s[2:3], 0, v[66:67]
	v_lshl_add_u64 v[66:67], v[66:67], 0, s[64:65]
	v_lshl_add_u64 v[66:67], v[66:67], 0, v[0:1]
	s_add_i32 s21, s21, s62
	s_add_i32 s20, s20, s1
	s_cmpk_gt_i32 s21, 0xff
	s_mov_b32 s25, 0x7f800000
	s_mov_b32 s46, 0xbfb8aa3b
	v_lshl_add_u64 v[66:67], v[66:67], 0, v[0:1]
	v_pk_mul_f32 v[34:35], v[34:35], v[68:69] op_sel_hi:[1,0]
	v_pk_mul_f32 v[36:37], v[36:37], v[68:69] op_sel_hi:[1,0]
	v_pk_mul_f32 v[38:39], v[38:39], v[68:69] op_sel_hi:[1,0]
	v_pk_mul_f32 v[40:41], v[40:41], v[68:69] op_sel_hi:[1,0]
	v_cvt_pk_bf16_f32 v34, v34, v35
	v_cvt_pk_bf16_f32 v35, v36, v37
	v_cvt_pk_bf16_f32 v36, v38, v39
	v_cvt_pk_bf16_f32 v37, v40, v41
	s_nop 1
	v_permlane32_swap_b32_e32 v34, v36
	v_permlane32_swap_b32_e32 v35, v37
	global_store_dwordx4 v[66:67], v[34:37], off
	v_pk_mul_f32 v[42:43], v[42:43], v[68:69] op_sel_hi:[1,0]
	v_pk_mul_f32 v[44:45], v[44:45], v[68:69] op_sel_hi:[1,0]
	v_pk_mul_f32 v[46:47], v[46:47], v[68:69] op_sel_hi:[1,0]
	v_pk_mul_f32 v[48:49], v[48:49], v[68:69] op_sel_hi:[1,0]
	v_cvt_pk_bf16_f32 v42, v42, v43
	v_cvt_pk_bf16_f32 v43, v44, v45
	v_cvt_pk_bf16_f32 v44, v46, v47
	v_cvt_pk_bf16_f32 v45, v48, v49
	s_nop 1
	v_permlane32_swap_b32_e32 v42, v44
	v_permlane32_swap_b32_e32 v43, v45
	global_store_dwordx4 v[66:67], v[42:45], off offset:32
	v_pk_mul_f32 v[50:51], v[50:51], v[68:69] op_sel_hi:[1,0]
	v_pk_mul_f32 v[52:53], v[52:53], v[68:69] op_sel_hi:[1,0]
	v_pk_mul_f32 v[54:55], v[54:55], v[68:69] op_sel_hi:[1,0]
	v_pk_mul_f32 v[56:57], v[56:57], v[68:69] op_sel_hi:[1,0]
	v_cvt_pk_bf16_f32 v50, v50, v51
	v_cvt_pk_bf16_f32 v51, v52, v53
	v_cvt_pk_bf16_f32 v52, v54, v55
	v_cvt_pk_bf16_f32 v53, v56, v57
	s_nop 1
	v_permlane32_swap_b32_e32 v50, v52
	v_permlane32_swap_b32_e32 v51, v53
	global_store_dwordx4 v[66:67], v[50:53], off offset:64
	v_pk_mul_f32 v[58:59], v[58:59], v[68:69] op_sel_hi:[1,0]
	v_pk_mul_f32 v[60:61], v[60:61], v[68:69] op_sel_hi:[1,0]
	v_pk_mul_f32 v[62:63], v[62:63], v[68:69] op_sel_hi:[1,0]
	v_pk_mul_f32 v[64:65], v[64:65], v[68:69] op_sel_hi:[1,0]
	v_cvt_pk_bf16_f32 v58, v58, v59
	v_cvt_pk_bf16_f32 v59, v60, v61
	v_cvt_pk_bf16_f32 v60, v62, v63
	v_cvt_pk_bf16_f32 v61, v64, v65
	s_nop 1
	v_permlane32_swap_b32_e32 v58, v60
	v_permlane32_swap_b32_e32 v59, v61
	global_store_dwordx4 v[66:67], v[58:61], off offset:96
	v_pk_mul_f32 v[18:19], v[18:19], v[68:69] op_sel_hi:[1,0]
	v_pk_mul_f32 v[20:21], v[20:21], v[68:69] op_sel_hi:[1,0]
	v_pk_mul_f32 v[22:23], v[22:23], v[68:69] op_sel_hi:[1,0]
	v_pk_mul_f32 v[24:25], v[24:25], v[68:69] op_sel_hi:[1,0]
	v_cvt_pk_bf16_f32 v18, v18, v19
	v_cvt_pk_bf16_f32 v19, v20, v21
	v_cvt_pk_bf16_f32 v20, v22, v23
	v_cvt_pk_bf16_f32 v21, v24, v25
	s_nop 1
	v_permlane32_swap_b32_e32 v18, v20
	v_permlane32_swap_b32_e32 v19, v21
	global_store_dwordx4 v[66:67], v[18:21], off offset:128
	v_pk_mul_f32 v[26:27], v[26:27], v[68:69] op_sel_hi:[1,0]
	v_pk_mul_f32 v[28:29], v[28:29], v[68:69] op_sel_hi:[1,0]
	v_pk_mul_f32 v[30:31], v[30:31], v[68:69] op_sel_hi:[1,0]
	v_pk_mul_f32 v[32:33], v[32:33], v[68:69] op_sel_hi:[1,0]
	v_cvt_pk_bf16_f32 v26, v26, v27
	v_cvt_pk_bf16_f32 v27, v28, v29
	v_cvt_pk_bf16_f32 v28, v30, v31
	v_cvt_pk_bf16_f32 v29, v32, v33
	s_nop 1
	v_permlane32_swap_b32_e32 v26, v28
	v_permlane32_swap_b32_e32 v27, v29
	global_store_dwordx4 v[66:67], v[26:29], off offset:160
	v_pk_mul_f32 v[2:3], v[2:3], v[68:69] op_sel_hi:[1,0]
	v_pk_mul_f32 v[4:5], v[4:5], v[68:69] op_sel_hi:[1,0]
	v_pk_mul_f32 v[6:7], v[6:7], v[68:69] op_sel_hi:[1,0]
	v_pk_mul_f32 v[8:9], v[8:9], v[68:69] op_sel_hi:[1,0]
	v_cvt_pk_bf16_f32 v2, v2, v3
	v_cvt_pk_bf16_f32 v3, v4, v5
	v_cvt_pk_bf16_f32 v4, v6, v7
	v_cvt_pk_bf16_f32 v5, v8, v9
	s_nop 1
	v_permlane32_swap_b32_e32 v2, v4
	v_permlane32_swap_b32_e32 v3, v5
	global_store_dwordx4 v[66:67], v[2:5], off offset:192
	v_pk_mul_f32 v[10:11], v[10:11], v[68:69] op_sel_hi:[1,0]
	v_pk_mul_f32 v[12:13], v[12:13], v[68:69] op_sel_hi:[1,0]
	v_pk_mul_f32 v[14:15], v[14:15], v[68:69] op_sel_hi:[1,0]
	v_pk_mul_f32 v[16:17], v[16:17], v[68:69] op_sel_hi:[1,0]
	v_cvt_pk_bf16_f32 v10, v10, v11
	v_cvt_pk_bf16_f32 v11, v12, v13
	v_cvt_pk_bf16_f32 v12, v14, v15
	v_cvt_pk_bf16_f32 v13, v16, v17
	s_nop 1
	v_permlane32_swap_b32_e32 v10, v12
	v_permlane32_swap_b32_e32 v11, v13
	global_store_dwordx4 v[66:67], v[10:13], off offset:224
	s_cbranch_scc1 .LBB0_223

; #define LAS __attribute__((address_space(3)))
; __device__ __forceinline__ unsigned cvtpk(float lo, float hi) { f32x2 v = {lo, hi}; bf16x2_t b = __builtin_convertvector(v, bf16x2_t); return __builtin_bit_cast(unsigned, b); }
; __device__ __forceinline__ int opaque_tid() { int t = threadIdx.x; asm volatile("" : "+v"(t)); return t; }
; #define ATT_DMAK(t) do { const int sl_ = (t) % NSLOT; _Pragma("unroll") for (int i = 0; i < 2; ++i) \
;         __builtin_amdgcn_global_load_lds((const unsigned*)(Kg + (size_t)(t) * 16384 + i * 1024), (LAS unsigned*)(lds + OFF_K + sl_ * KBUF + wid * 2048 + i * 1024), 16, 0, 0); } while (0)
; #define ATT_DMAV(t) do { const int sl_ = (t) % NSLOT; _Pragma("unroll") for (int i = 0; i < 2; ++i) \
;         __builtin_amdgcn_global_load_lds((const unsigned*)(Vg + (size_t)(t) * 16384 + i * 1024), (LAS unsigned*)(lds + OFF_V + sl_ * VBUF + wid * 2048 + i * 1024), 16, 0, 0); } while (0)
; __device__ __forceinline__ void attn_unit(LAS unsigned char* lds, int b, int hh, int qb, const bf16_t* QK, const bf16_t* VT, bf16_t* CAT) {
;     const int tid = opaque_tid(), lane = tid & 63, r32 = lane & 31, hi = lane >> 5; const int wid = __builtin_amdgcn_readfirstlane(tid >> 6);
;     const bool fox = hh < NH;
;     const bool lead = wid < 4;
;     const int qch = fox ? hh : hh + 8, kch = qch + 8;
;     const int q0 = qb * 256 + wid * 32, qpos = q0 + r32;
;     const LAS float* tab = (const LAS float*)(lds + OFF_TAB);
;     const float C = 0.08838834764831845f * LOG2E;
;     const int nt = (qb + 1) * 4;
;     const char* Kg = (const char*)(QK + (size_t)(b * 32 + kch) * SEQ * HD) + wid * 2048 + lane * 16;
;     const char* Vg = (const char*)(VT + (size_t)(b * 16 + hh) * SEQ * HD) + wid * 2048 + lane * 16;
;     ...
;     ATT_DMAK(0); ATT_DMAK(1); ATT_DMAV(0);
;     ...
;     lrun += __shfl_xor(lrun, 32);
;     const float inv = 1.0f / lrun;
;     bf16_t* Op = CAT + (size_t)(b * SEQ + qpos) * DM + hh * HD + 4 * hi;
; #pragma unroll
;     for (int d = 0; d < 4; ++d)
; #pragma unroll
;         for (int g = 0; g < 4; ++g) { u32x2 w; w.x = cvtpk(o[d][4 * g] * inv, o[d][4 * g + 1] * inv); w.y = cvtpk(o[d][4 * g + 2] * inv, o[d][4 * g + 3] * inv);
;             *(u32x2*)(Op + 32 * d + 8 * g) = w; }
.LBB0_319:
	v_xor_b32_e32 v0, 32, v204
	v_add_u32_e32 v2, 64, v205
	v_cmp_lt_i32_e32 vcc, v0, v2
	s_bfe_u32 s26, s20, 0x10001
	s_lshl_b32 s2, s26, 3
	v_cndmask_b32_e32 v0, v204, v0, vcc
	v_lshlrev_b32_e32 v175, 2, v0
	ds_bpermute_b32 v0, v175, v193
	s_xor_b32 s46, s2, 29
	s_lshl_b32 s29, s27, 11
	s_lshl_b32 s28, s64, 7
	s_lshl_b32 s64, s64, 8
	s_waitcnt lgkmcnt(0)
	v_add_f32_e32 v0, v193, v0
	v_div_scale_f32 v2, s[2:3], v0, v0, 1.0
	v_rcp_f32_e32 v3, v2
	v_readlane_b32 s2, v250, 53
	v_readlane_b32 s3, v250, 54
	v_mov_b32_e32 v163, v1
	v_fma_f32 v4, -v2, v3, 1.0
	v_fmac_f32_e32 v3, v4, v3
	v_div_scale_f32 v4, vcc, 1.0, v0, 1.0
	v_mul_f32_e32 v5, v4, v3
	v_fma_f32 v6, -v2, v5, v4
	v_fmac_f32_e32 v5, v6, v3
	v_fma_f32 v2, -v2, v5, v4
	v_div_fmas_f32 v2, v2, v3, v5
	v_div_fixup_f32 v0, v2, v0, 1.0
	s_nop 1
	v_add_u32_e32 v2, s29, v160
	v_ashrrev_i32_e32 v3, 31, v2
	v_lshlrev_b64 v[2:3], 12, v[2:3]
	v_lshl_add_u64 v[2:3], s[2:3], 0, v[2:3]
	v_lshl_add_u64 v[2:3], v[2:3], 0, s[64:65]
	v_lshl_add_u64 v[2:3], v[2:3], 0, v[162:163]
	v_mov_b32_e32 v8, v166
	v_lshl_add_u64 v[2:3], v[2:3], 0, v[162:163]
	v_pk_mul_f32 v[64:65], v[64:65], v[0:1] op_sel_hi:[1,0]
	v_pk_mul_f32 v[66:67], v[66:67], v[0:1] op_sel_hi:[1,0]
	v_pk_mul_f32 v[68:69], v[68:69], v[0:1] op_sel_hi:[1,0]
	v_pk_mul_f32 v[70:71], v[70:71], v[0:1] op_sel_hi:[1,0]
	v_cvt_pk_bf16_f32 v64, v64, v65
	v_cvt_pk_bf16_f32 v65, v66, v67
	v_cvt_pk_bf16_f32 v66, v68, v69
	v_cvt_pk_bf16_f32 v67, v70, v71
	s_nop 1
	v_permlane32_swap_b32_e32 v64, v66
	v_permlane32_swap_b32_e32 v65, v67
	global_store_dwordx4 v[2:3], v[64:67], off
	v_pk_mul_f32 v[72:73], v[72:73], v[0:1] op_sel_hi:[1,0]
	v_pk_mul_f32 v[74:75], v[74:75], v[0:1] op_sel_hi:[1,0]
	v_pk_mul_f32 v[76:77], v[76:77], v[0:1] op_sel_hi:[1,0]
	v_pk_mul_f32 v[78:79], v[78:79], v[0:1] op_sel_hi:[1,0]
	v_cvt_pk_bf16_f32 v72, v72, v73
	v_cvt_pk_bf16_f32 v73, v74, v75
	v_cvt_pk_bf16_f32 v74, v76, v77
	v_cvt_pk_bf16_f32 v75, v78, v79
	s_nop 1
	v_permlane32_swap_b32_e32 v72, v74
	v_permlane32_swap_b32_e32 v73, v75
	global_store_dwordx4 v[2:3], v[72:75], off offset:32
	v_pk_mul_f32 v[48:49], v[48:49], v[0:1] op_sel_hi:[1,0]
	v_pk_mul_f32 v[50:51], v[50:51], v[0:1] op_sel_hi:[1,0]
	v_pk_mul_f32 v[52:53], v[52:53], v[0:1] op_sel_hi:[1,0]
	v_pk_mul_f32 v[54:55], v[54:55], v[0:1] op_sel_hi:[1,0]
	v_cvt_pk_bf16_f32 v48, v48, v49
	v_cvt_pk_bf16_f32 v49, v50, v51
	v_cvt_pk_bf16_f32 v50, v52, v53
	v_cvt_pk_bf16_f32 v51, v54, v55
	s_nop 1
	v_permlane32_swap_b32_e32 v48, v50
	v_permlane32_swap_b32_e32 v49, v51
	global_store_dwordx4 v[2:3], v[48:51], off offset:64
	v_pk_mul_f32 v[56:57], v[56:57], v[0:1] op_sel_hi:[1,0]
	v_pk_mul_f32 v[58:59], v[58:59], v[0:1] op_sel_hi:[1,0]
	v_pk_mul_f32 v[60:61], v[60:61], v[0:1] op_sel_hi:[1,0]
	v_pk_mul_f32 v[62:63], v[62:63], v[0:1] op_sel_hi:[1,0]
	v_cvt_pk_bf16_f32 v56, v56, v57
	v_cvt_pk_bf16_f32 v57, v58, v59
	v_cvt_pk_bf16_f32 v58, v60, v61
	v_cvt_pk_bf16_f32 v59, v62, v63
	s_nop 1
	v_permlane32_swap_b32_e32 v56, v58
	v_permlane32_swap_b32_e32 v57, v59
	global_store_dwordx4 v[2:3], v[56:59], off offset:96
	v_pk_mul_f32 v[32:33], v[32:33], v[0:1] op_sel_hi:[1,0]
	v_pk_mul_f32 v[34:35], v[34:35], v[0:1] op_sel_hi:[1,0]
	v_pk_mul_f32 v[36:37], v[36:37], v[0:1] op_sel_hi:[1,0]
	v_pk_mul_f32 v[38:39], v[38:39], v[0:1] op_sel_hi:[1,0]
	v_cvt_pk_bf16_f32 v32, v32, v33
	v_cvt_pk_bf16_f32 v33, v34, v35
	v_cvt_pk_bf16_f32 v34, v36, v37
	v_cvt_pk_bf16_f32 v35, v38, v39
	s_nop 1
	v_permlane32_swap_b32_e32 v32, v34
	v_permlane32_swap_b32_e32 v33, v35
	global_store_dwordx4 v[2:3], v[32:35], off offset:128
	v_pk_mul_f32 v[40:41], v[40:41], v[0:1] op_sel_hi:[1,0]
	v_pk_mul_f32 v[42:43], v[42:43], v[0:1] op_sel_hi:[1,0]
	v_pk_mul_f32 v[44:45], v[44:45], v[0:1] op_sel_hi:[1,0]
	v_pk_mul_f32 v[46:47], v[46:47], v[0:1] op_sel_hi:[1,0]
	v_cvt_pk_bf16_f32 v40, v40, v41
	v_cvt_pk_bf16_f32 v41, v42, v43
	v_cvt_pk_bf16_f32 v42, v44, v45
	v_cvt_pk_bf16_f32 v43, v46, v47
	s_nop 1
	v_permlane32_swap_b32_e32 v40, v42
	v_permlane32_swap_b32_e32 v41, v43
	global_store_dwordx4 v[2:3], v[40:43], off offset:160
	v_pk_mul_f32 v[16:17], v[16:17], v[0:1] op_sel_hi:[1,0]
	v_pk_mul_f32 v[18:19], v[18:19], v[0:1] op_sel_hi:[1,0]
	v_pk_mul_f32 v[20:21], v[20:21], v[0:1] op_sel_hi:[1,0]
	v_pk_mul_f32 v[22:23], v[22:23], v[0:1] op_sel_hi:[1,0]
	v_cvt_pk_bf16_f32 v16, v16, v17
	v_cvt_pk_bf16_f32 v17, v18, v19
	v_cvt_pk_bf16_f32 v18, v20, v21
	v_cvt_pk_bf16_f32 v19, v22, v23
	s_nop 1
	v_permlane32_swap_b32_e32 v16, v18
	v_permlane32_swap_b32_e32 v17, v19
	global_store_dwordx4 v[2:3], v[16:19], off offset:192
	v_pk_mul_f32 v[24:25], v[24:25], v[0:1] op_sel_hi:[1,0]
	v_pk_mul_f32 v[26:27], v[26:27], v[0:1] op_sel_hi:[1,0]
	v_pk_mul_f32 v[28:29], v[28:29], v[0:1] op_sel_hi:[1,0]
	v_pk_mul_f32 v[30:31], v[30:31], v[0:1] op_sel_hi:[1,0]
	v_cvt_pk_bf16_f32 v24, v24, v25
	v_cvt_pk_bf16_f32 v25, v26, v27
	v_cvt_pk_bf16_f32 v26, v28, v29
	v_cvt_pk_bf16_f32 v27, v30, v31
	s_nop 1
	v_permlane32_swap_b32_e32 v24, v26
	v_permlane32_swap_b32_e32 v25, v27
	global_store_dwordx4 v[2:3], v[24:27], off offset:224
	s_sub_i32 s2, 6, s22
	v_readfirstlane_b32 s3, v8
	s_ashr_i32 s10, s3, 6
	s_lshl_b32 s3, s2, 8
	s_lshl_b32 s52, s10, 5
	s_lshl_b32 s11, s2, 2
	s_lshl_b32 s2, s10, 11
	s_lshl_b32 s1, s26, 11
	s_add_i32 s52, s52, s3
	s_ashr_i32 s3, s2, 31
	s_add_u32 s4, s23, s2
	s_addc_u32 s5, s24, s3
	s_add_u32 s8, s25, s2
	v_and_b32_e32 v0, 63, v8
	s_addc_u32 s9, s50, s3
	s_add_i32 s53, s2, 0
	v_lshlrev_b32_e32 v0, 4, v0
	s_mov_b32 m0, s53
	v_lshl_add_u64 v[2:3], s[4:5], 0, v[0:1]
	global_load_lds_dwordx4 v0, s[4:5]
	s_add_i32 m0, s53, 0x400
	s_mov_b64 s[12:13], 0x400
	s_cmp_gt_i32 s10, 3
; __device__ __forceinline__ int pi32(int rho) { return (rho & 0x13) | ((rho & 4) << 1) | ((rho & 8) >> 1); }
; #define ATT_DMAK(t) do { const int sl_ = (t) % NSLOT; _Pragma("unroll") for (int i = 0; i < 2; ++i) \
;         __builtin_amdgcn_global_load_lds((const unsigned*)(Kg + (size_t)(t) * 16384 + i * 1024), (LAS unsigned*)(lds + OFF_K + sl_ * KBUF + wid * 2048 + i * 1024), 16, 0, 0); } while (0)
; #define ATT_DMAV(t) do { const int sl_ = (t) % NSLOT; _Pragma("unroll") for (int i = 0; i < 2; ++i) \
;         __builtin_amdgcn_global_load_lds((const unsigned*)(Vg + (size_t)(t) * 16384 + i * 1024), (LAS unsigned*)(lds + OFF_V + sl_ * VBUF + wid * 2048 + i * 1024), 16, 0, 0); } while (0)
; __device__ __forceinline__ void attn_unit(LAS unsigned char* lds, int b, int hh, int qb, const bf16_t* QK, const bf16_t* VT, bf16_t* CAT) {
;     ...
;     const char* Kg = (const char*)(QK + (size_t)(b * 32 + kch) * SEQ * HD) + wid * 2048 + lane * 16;
;     const char* Vg = (const char*)(VT + (size_t)(b * 16 + hh) * SEQ * HD) + wid * 2048 + lane * 16;
;     ...
;     ATT_DMAK(0); ATT_DMAK(1); ATT_DMAV(0);
;     bf16x8 qf[8];
;     { const bf16_t* Qp = QK + ((size_t)(b * 32 + qch) * SEQ + qpos) * HD;
; #pragma unroll
;       for (int d0 = 0; d0 < 8; ++d0) qf[d0] = *(const bf16x8*)(Qp + (((2 * d0 + hi) ^ (qpos & 15)) << 3)); }
;     const int krow = pi32(r32);
;     int koff[8];
; #pragma unroll
;     for (int d0 = 0; d0 < 8; ++d0) koff[d0] = krow * 256 + (((2 * d0 + hi) ^ (krow & 15)) << 4);
;     int voff[4];
; #pragma unroll
;     for (int c = 0; c < 4; ++c) voff[c] = r32 * 128 + (((2 * c + hi) ^ ((r32 >> 1) & 7)) << 4);
;     f32x16 o[4];
; #pragma unroll
;     for (int d = 0; d < 4; ++d)
; #pragma unroll
;         for (int i = 0; i < 16; ++i) o[d][i] = 0.f;
;     float mrun = -1e30f, lrun = 0.f;
;     f32x16 s0, s1;
;     bf16x8 pf[4];
;     bool v0 = false, v1 = false, pv0 = false, pv1 = false;
; #pragma unroll
;     for (int i = 0; i < 16; ++i) { s0[i] = 0.f; s1[i] = 0.f; }
; #pragma unroll
;     for (int i = 0; i < 4; ++i) pf[i] = (bf16x8){0, 0, 0, 0, 0, 0, 0, 0};
	v_lshl_add_u64 v[4:5], v[2:3], 0, s[12:13]
	s_cselect_b64 s[4:5], -1, 0
	s_cmp_lt_i32 s10, 4
	global_load_lds_dwordx4 v[4:5], off
	s_cselect_b64 s[6:7], -1, 0
	v_lshl_add_u64 v[4:5], v[2:3], 0, s[74:75]
	s_add_i32 m0, s53, 0x4000
	s_mov_b64 s[14:15], 0x4400
	v_and_b32_e32 v9, 31, v8
	global_load_lds_dwordx4 v[4:5], off
	v_lshl_add_u64 v[2:3], v[2:3], 0, s[14:15]
	s_add_i32 m0, s53, 0x4400
	v_or_b32_e32 v160, s52, v9
	global_load_lds_dwordx4 v[2:3], off
	v_lshl_add_u64 v[2:3], s[8:9], 0, v[0:1]
	s_add_i32 m0, s53, 0xc000
	v_bfe_u32 v10, v8, 5, 1
	global_load_lds_dwordx4 v0, s[8:9]
	v_lshl_add_u64 v[2:3], v[2:3], 0, s[12:13]
	s_add_i32 m0, s53, 0xc400
	v_ashrrev_i32_e32 v161, 31, v160
	global_load_lds_dwordx4 v[2:3], off
	v_lshlrev_b64 v[2:3], 8, v[160:161]
	v_and_b32_e32 v11, 15, v8
	v_bitop3_b32 v4, v10, v8, 15 bitop3:0x78
	v_lshl_add_u64 v[2:3], s[54:55], 0, v[2:3]
	v_lshlrev_b32_e32 v4, 4, v4
	v_mov_b32_e32 v5, v1
	v_bitop3_b32 v6, v10, v11, 2 bitop3:0x36
	v_lshl_add_u64 v[4:5], v[2:3], 0, v[4:5]
	v_lshlrev_b32_e32 v6, 4, v6
	v_mov_b32_e32 v7, v1
	v_lshl_add_u64 v[6:7], v[2:3], 0, v[6:7]
	global_load_dwordx4 v[112:115], v[4:5], off
	global_load_dwordx4 v[116:119], v[6:7], off
	v_bitop3_b32 v4, v10, v11, 4 bitop3:0x36
	v_lshlrev_b32_e32 v4, 4, v4
	v_mov_b32_e32 v5, v1
	v_bitop3_b32 v6, v10, v11, 6 bitop3:0x36
	v_lshl_add_u64 v[4:5], v[2:3], 0, v[4:5]
	v_lshlrev_b32_e32 v6, 4, v6
	v_mov_b32_e32 v7, v1
	v_lshl_add_u64 v[6:7], v[2:3], 0, v[6:7]
	global_load_dwordx4 v[120:123], v[4:5], off
	global_load_dwordx4 v[124:127], v[6:7], off
	v_bitop3_b32 v4, v10, v11, 8 bitop3:0x36
	v_lshlrev_b32_e32 v4, 4, v4
	v_mov_b32_e32 v5, v1
	v_bitop3_b32 v6, v10, v11, 10 bitop3:0x36
	v_lshl_add_u64 v[4:5], v[2:3], 0, v[4:5]
	v_lshlrev_b32_e32 v6, 4, v6
	v_mov_b32_e32 v7, v1
	v_lshl_add_u64 v[6:7], v[2:3], 0, v[6:7]
	global_load_dwordx4 v[128:131], v[4:5], off
	global_load_dwordx4 v[132:135], v[6:7], off
	v_bitop3_b32 v4, v10, v11, 12 bitop3:0x36
	v_lshlrev_b32_e32 v4, 4, v4
	v_mov_b32_e32 v5, v1
	v_bitop3_b32 v6, v10, v11, 14 bitop3:0x36
	v_lshl_add_u64 v[4:5], v[2:3], 0, v[4:5]
	v_lshlrev_b32_e32 v6, 4, v6
	v_mov_b32_e32 v7, v1
	v_lshl_add_u64 v[2:3], v[2:3], 0, v[6:7]
	global_load_dwordx4 v[136:139], v[4:5], off
	global_load_dwordx4 v[140:143], v[2:3], off
	v_lshlrev_b32_e32 v3, 1, v8
	v_lshrrev_b32_e32 v4, 1, v8
	v_and_b32_e32 v2, 19, v8
	v_and_b32_e32 v3, 8, v3
	v_and_b32_e32 v5, 4, v4
	v_or3_b32 v6, v5, v2, v3
	v_or_b32_e32 v12, 2, v10
	v_bitop3_b32 v7, v6, v10, 15 bitop3:0x6c
	v_or_b32_e32 v13, 4, v10
	v_lshlrev_b32_e32 v163, 4, v7
	v_bitop3_b32 v7, v6, v12, 15 bitop3:0x6c
	v_or_b32_e32 v14, 6, v10
	v_lshlrev_b32_e32 v178, 4, v7
	v_bitop3_b32 v7, v6, v13, 15 bitop3:0x6c
	v_or_b32_e32 v15, 8, v10
	v_lshlrev_b32_e32 v179, 4, v7
	v_bitop3_b32 v7, v6, v14, 15 bitop3:0x6c
	v_or_b32_e32 v16, 10, v10
	v_lshlrev_b32_e32 v180, 4, v7
	v_bitop3_b32 v7, v6, v15, 15 bitop3:0x6c
	v_or_b32_e32 v17, 12, v10
	v_or_b32_e32 v18, 14, v10
	v_lshlrev_b32_e32 v181, 4, v7
	v_bitop3_b32 v7, v6, v16, 15 bitop3:0x6c
	s_or_b32 s58, s11, 4
	v_lshlrev_b32_e32 v182, 4, v7
	v_bitop3_b32 v7, v6, v17, 15 bitop3:0x6c
	v_bitop3_b32 v6, v6, v18, 15 bitop3:0x6c
	s_or_b32 s63, s52, 31
	s_or_b32 s64, s52, 1
	v_lshlrev_b32_e32 v184, 4, v6
	v_bfe_u32 v6, v8, 1, 3
	v_bitop3_b32 v4, v10, v4, 7 bitop3:0x78
	s_add_u32 s8, s60, s92
	v_lshlrev_b32_e32 v185, 4, v4
	v_bitop3_b32 v4, v10, v6, 2 bitop3:0x36
	s_addc_u32 s9, s61, s93
	v_lshlrev_b32_e32 v186, 4, v4
	v_bitop3_b32 v4, v10, v6, 4 bitop3:0x36
	v_lshl_add_u64 v[164:165], s[8:9], 0, v[0:1]
	s_add_u32 s8, s60, s56
	v_lshlrev_b32_e32 v187, 4, v4
	v_bitop3_b32 v4, v10, v6, 6 bitop3:0x36
	v_and_b32_e32 v189, 32, v8
	s_addc_u32 s9, s61, s57
	v_lshlrev_b32_e32 v188, 4, v4
	v_lshl_add_u64 v[176:177], s[8:9], 0, v[0:1]
	v_or_b32_e32 v0, s1, v189
	v_lshlrev_b32_e32 v4, 2, v9
	v_sub_u32_e32 v0, v0, v4
	s_lshl_b32 s8, s10, 7
	s_waitcnt vmcnt(0) lgkmcnt(0)
	s_barrier
	v_subrev_u32_e32 v190, s8, v0
	v_or3_b32 v0, v2, v3, v5
	v_mov_b32_e32 v14, v1
	v_mov_b32_e32 v15, v1
	v_lshlrev_b32_e32 v183, 4, v7
	v_lshlrev_b32_e32 v162, 3, v10
	v_lshl_add_u32 v191, v0, 8, 0
	v_lshl_add_u32 v192, v9, 7, 0
	v_mov_b32_e32 v0, v1
	v_mov_b32_e32 v2, v1
	v_mov_b32_e32 v3, v1
	v_mov_b32_e32 v4, v1
	v_mov_b32_e32 v5, v1
	v_mov_b32_e32 v6, v1
	v_mov_b32_e32 v7, v1
	v_mov_b32_e32 v8, v1
	v_mov_b32_e32 v9, v1
	v_mov_b32_e32 v10, v1
	v_mov_b32_e32 v11, v1
	v_mov_b32_e32 v12, v1
	v_mov_b32_e32 v13, v1
	v_mov_b64_e32 v[78:79], v[14:15]
	v_mov_b64_e32 v[62:63], v[14:15]
	v_mov_b64_e32 v[46:47], v[14:15]
	v_mov_b64_e32 v[30:31], v[14:15]
	v_mov_b64_e32 v[110:111], v[14:15]
	v_mov_b64_e32 v[94:95], v[14:15]
	s_mov_b32 s48, 0
	s_mov_b32 s49, -1
	s_mov_b32 s51, 2
	s_mov_b32 s27, 63
	s_mov_b32 s59, 1
	v_mov_b32_e32 v161, v160
	s_mov_b64 s[8:9], 0
	v_mov_b32_e32 v195, 0xf149f2ca
	v_mov_b32_e32 v194, 0
	v_mov_b32_e32 v152, 0
	v_mov_b32_e32 v153, 0
	v_mov_b32_e32 v154, 0
	v_mov_b32_e32 v155, 0
	v_mov_b32_e32 v156, 0
	v_mov_b32_e32 v157, 0
	v_mov_b32_e32 v158, 0
	v_mov_b32_e32 v159, 0
	v_mov_b32_e32 v144, 0
	v_mov_b32_e32 v145, 0
	v_mov_b32_e32 v146, 0
	v_mov_b32_e32 v147, 0
	v_mov_b32_e32 v148, 0
	v_mov_b32_e32 v149, 0
	v_mov_b32_e32 v150, 0
	v_mov_b32_e32 v151, 0
	v_mov_b32_e32 v193, v189
	v_mov_b64_e32 v[76:77], v[12:13]
	v_mov_b64_e32 v[74:75], v[10:11]
	v_mov_b64_e32 v[72:73], v[8:9]
	v_mov_b64_e32 v[70:71], v[6:7]
	v_mov_b64_e32 v[68:69], v[4:5]
	v_mov_b64_e32 v[66:67], v[2:3]
	v_mov_b64_e32 v[64:65], v[0:1]
	v_mov_b64_e32 v[60:61], v[12:13]
	v_mov_b64_e32 v[58:59], v[10:11]
	v_mov_b64_e32 v[56:57], v[8:9]
	v_mov_b64_e32 v[54:55], v[6:7]
	v_mov_b64_e32 v[52:53], v[4:5]
	v_mov_b64_e32 v[50:51], v[2:3]
	v_mov_b64_e32 v[48:49], v[0:1]
	v_mov_b64_e32 v[44:45], v[12:13]
	v_mov_b64_e32 v[42:43], v[10:11]
	v_mov_b64_e32 v[40:41], v[8:9]
	v_mov_b64_e32 v[38:39], v[6:7]
	v_mov_b64_e32 v[36:37], v[4:5]
	v_mov_b64_e32 v[34:35], v[2:3]
	v_mov_b64_e32 v[32:33], v[0:1]
	v_mov_b64_e32 v[28:29], v[12:13]
	v_mov_b64_e32 v[26:27], v[10:11]
	v_mov_b64_e32 v[24:25], v[8:9]
	v_mov_b64_e32 v[22:23], v[6:7]
	v_mov_b64_e32 v[20:21], v[4:5]
	v_mov_b64_e32 v[18:19], v[2:3]
	v_mov_b64_e32 v[16:17], v[0:1]
	v_mov_b64_e32 v[108:109], v[12:13]
	v_mov_b64_e32 v[106:107], v[10:11]
	v_mov_b64_e32 v[104:105], v[8:9]
	v_mov_b64_e32 v[102:103], v[6:7]
	v_mov_b64_e32 v[100:101], v[4:5]
	v_mov_b64_e32 v[98:99], v[2:3]
	v_mov_b64_e32 v[96:97], v[0:1]
	v_mov_b64_e32 v[92:93], v[12:13]
	v_mov_b64_e32 v[90:91], v[10:11]
	v_mov_b64_e32 v[88:89], v[8:9]
	v_mov_b64_e32 v[86:87], v[6:7]
	v_mov_b64_e32 v[84:85], v[4:5]
	v_mov_b64_e32 v[82:83], v[2:3]
	v_mov_b64_e32 v[80:81], v[0:1]
	s_mov_b64 s[10:11], 0
	s_mov_b64 s[18:19], 0
	s_mov_b64 s[16:17], 0
	s_mov_b32 s67, 0
	s_waitcnt vmcnt(0)

; #define LAS __attribute__((address_space(3)))
; __device__ __forceinline__ unsigned cvtpk(float lo, float hi) { f32x2 v = {lo, hi}; bf16x2_t b = __builtin_convertvector(v, bf16x2_t); return __builtin_bit_cast(unsigned, b); }
; __device__ __forceinline__ int opaque_tid() { int t = threadIdx.x; asm volatile("" : "+v"(t)); return t; }
; #define ATT_DMAK(t) do { const int sl_ = (t) % NSLOT; _Pragma("unroll") for (int i = 0; i < 2; ++i) \
;         __builtin_amdgcn_global_load_lds((const unsigned*)(Kg + (size_t)(t) * 16384 + i * 1024), (LAS unsigned*)(lds + OFF_K + sl_ * KBUF + wid * 2048 + i * 1024), 16, 0, 0); } while (0)
; #define ATT_DMAV(t) do { const int sl_ = (t) % NSLOT; _Pragma("unroll") for (int i = 0; i < 2; ++i) \
;         __builtin_amdgcn_global_load_lds((const unsigned*)(Vg + (size_t)(t) * 16384 + i * 1024), (LAS unsigned*)(lds + OFF_V + sl_ * VBUF + wid * 2048 + i * 1024), 16, 0, 0); } while (0)
; __device__ __forceinline__ void attn_unit(LAS unsigned char* lds, int b, int hh, int qb, const bf16_t* QK, const bf16_t* VT, bf16_t* CAT) {
;     const int tid = opaque_tid(), lane = tid & 63, r32 = lane & 31, hi = lane >> 5; const int wid = __builtin_amdgcn_readfirstlane(tid >> 6);
;     const bool fox = hh < NH;
;     const bool lead = wid < 4;
;     const int qch = fox ? hh : hh + 8, kch = qch + 8;
;     const int q0 = qb * 256 + wid * 32, qpos = q0 + r32;
;     const LAS float* tab = (const LAS float*)(lds + OFF_TAB);
;     const float C = 0.08838834764831845f * LOG2E;
;     const int nt = (qb + 1) * 4;
;     const char* Kg = (const char*)(QK + (size_t)(b * 32 + kch) * SEQ * HD) + wid * 2048 + lane * 16;
;     const char* Vg = (const char*)(VT + (size_t)(b * 16 + hh) * SEQ * HD) + wid * 2048 + lane * 16;
;     ...
;     ATT_DMAK(0); ATT_DMAK(1); ATT_DMAV(0);
;     ...
;     lrun += __shfl_xor(lrun, 32);
;     const float inv = 1.0f / lrun;
;     bf16_t* Op = CAT + (size_t)(b * SEQ + qpos) * DM + hh * HD + 4 * hi;
; #pragma unroll
;     for (int d = 0; d < 4; ++d)
; #pragma unroll
;         for (int g = 0; g < 4; ++g) { u32x2 w; w.x = cvtpk(o[d][4 * g] * inv, o[d][4 * g + 1] * inv); w.y = cvtpk(o[d][4 * g + 2] * inv, o[d][4 * g + 3] * inv);
;             *(u32x2*)(Op + 32 * d + 8 * g) = w; }
.LBB0_393:
	ds_bpermute_b32 v0, v175, v194
	v_add_u32_e32 v2, s29, v160
	s_lshl_b32 s64, s28, 1
	v_mov_b32_e32 v163, v1
	v_mov_b32_e32 v8, v166
	s_waitcnt lgkmcnt(0)
	v_add_f32_e32 v0, v194, v0
	v_div_scale_f32 v3, s[2:3], v0, v0, 1.0
	v_rcp_f32_e32 v4, v3
	v_div_scale_f32 v5, vcc, 1.0, v0, 1.0
	v_readlane_b32 s2, v250, 53
	v_fma_f32 v6, -v3, v4, 1.0
	v_fmac_f32_e32 v4, v6, v4
	v_mul_f32_e32 v6, v5, v4
	v_fma_f32 v7, -v3, v6, v5
	v_fmac_f32_e32 v6, v7, v4
	v_fma_f32 v3, -v3, v6, v5
	v_div_fmas_f32 v3, v3, v4, v6
	v_div_fixup_f32 v0, v3, v0, 1.0
	s_nop 1
	v_ashrrev_i32_e32 v3, 31, v2
	v_lshlrev_b64 v[2:3], 12, v[2:3]
	v_readlane_b32 s3, v250, 54
	v_lshl_add_u64 v[2:3], s[2:3], 0, v[2:3]
	v_lshl_add_u64 v[2:3], v[2:3], 0, s[64:65]
	v_lshl_add_u64 v[2:3], v[2:3], 0, v[162:163]
	v_lshl_add_u64 v[2:3], v[2:3], 0, v[162:163]
	v_pk_mul_f32 v[64:65], v[64:65], v[0:1] op_sel_hi:[1,0]
	v_pk_mul_f32 v[66:67], v[66:67], v[0:1] op_sel_hi:[1,0]
	v_pk_mul_f32 v[68:69], v[68:69], v[0:1] op_sel_hi:[1,0]
	v_pk_mul_f32 v[70:71], v[70:71], v[0:1] op_sel_hi:[1,0]
	v_cvt_pk_bf16_f32 v64, v64, v65
	v_cvt_pk_bf16_f32 v65, v66, v67
	v_cvt_pk_bf16_f32 v66, v68, v69
	v_cvt_pk_bf16_f32 v67, v70, v71
	s_nop 1
	v_permlane32_swap_b32_e32 v64, v66
	v_permlane32_swap_b32_e32 v65, v67
	global_store_dwordx4 v[2:3], v[64:67], off
	v_pk_mul_f32 v[72:73], v[72:73], v[0:1] op_sel_hi:[1,0]
	v_pk_mul_f32 v[74:75], v[74:75], v[0:1] op_sel_hi:[1,0]
	v_pk_mul_f32 v[76:77], v[76:77], v[0:1] op_sel_hi:[1,0]
	v_pk_mul_f32 v[78:79], v[78:79], v[0:1] op_sel_hi:[1,0]
	v_cvt_pk_bf16_f32 v72, v72, v73
	v_cvt_pk_bf16_f32 v73, v74, v75
	v_cvt_pk_bf16_f32 v74, v76, v77
	v_cvt_pk_bf16_f32 v75, v78, v79
	s_nop 1
	v_permlane32_swap_b32_e32 v72, v74
	v_permlane32_swap_b32_e32 v73, v75
	global_store_dwordx4 v[2:3], v[72:75], off offset:32
	v_pk_mul_f32 v[48:49], v[48:49], v[0:1] op_sel_hi:[1,0]
	v_pk_mul_f32 v[50:51], v[50:51], v[0:1] op_sel_hi:[1,0]
	v_pk_mul_f32 v[52:53], v[52:53], v[0:1] op_sel_hi:[1,0]
	v_pk_mul_f32 v[54:55], v[54:55], v[0:1] op_sel_hi:[1,0]
	v_cvt_pk_bf16_f32 v48, v48, v49
	v_cvt_pk_bf16_f32 v49, v50, v51
	v_cvt_pk_bf16_f32 v50, v52, v53
	v_cvt_pk_bf16_f32 v51, v54, v55
	s_nop 1
	v_permlane32_swap_b32_e32 v48, v50
	v_permlane32_swap_b32_e32 v49, v51
	global_store_dwordx4 v[2:3], v[48:51], off offset:64
	v_pk_mul_f32 v[56:57], v[56:57], v[0:1] op_sel_hi:[1,0]
	v_pk_mul_f32 v[58:59], v[58:59], v[0:1] op_sel_hi:[1,0]
	v_pk_mul_f32 v[60:61], v[60:61], v[0:1] op_sel_hi:[1,0]
	v_pk_mul_f32 v[62:63], v[62:63], v[0:1] op_sel_hi:[1,0]
	v_cvt_pk_bf16_f32 v56, v56, v57
	v_cvt_pk_bf16_f32 v57, v58, v59
	v_cvt_pk_bf16_f32 v58, v60, v61
	v_cvt_pk_bf16_f32 v59, v62, v63
	s_nop 1
	v_permlane32_swap_b32_e32 v56, v58
	v_permlane32_swap_b32_e32 v57, v59
	global_store_dwordx4 v[2:3], v[56:59], off offset:96
	v_pk_mul_f32 v[32:33], v[32:33], v[0:1] op_sel_hi:[1,0]
	v_pk_mul_f32 v[34:35], v[34:35], v[0:1] op_sel_hi:[1,0]
	v_pk_mul_f32 v[36:37], v[36:37], v[0:1] op_sel_hi:[1,0]
	v_pk_mul_f32 v[38:39], v[38:39], v[0:1] op_sel_hi:[1,0]
	v_cvt_pk_bf16_f32 v32, v32, v33
	v_cvt_pk_bf16_f32 v33, v34, v35
	v_cvt_pk_bf16_f32 v34, v36, v37
	v_cvt_pk_bf16_f32 v35, v38, v39
	s_nop 1
	v_permlane32_swap_b32_e32 v32, v34
	v_permlane32_swap_b32_e32 v33, v35
	global_store_dwordx4 v[2:3], v[32:35], off offset:128
	v_pk_mul_f32 v[40:41], v[40:41], v[0:1] op_sel_hi:[1,0]
	v_pk_mul_f32 v[42:43], v[42:43], v[0:1] op_sel_hi:[1,0]
	v_pk_mul_f32 v[44:45], v[44:45], v[0:1] op_sel_hi:[1,0]
	v_pk_mul_f32 v[46:47], v[46:47], v[0:1] op_sel_hi:[1,0]
	v_cvt_pk_bf16_f32 v40, v40, v41
	v_cvt_pk_bf16_f32 v41, v42, v43
	v_cvt_pk_bf16_f32 v42, v44, v45
	v_cvt_pk_bf16_f32 v43, v46, v47
	s_nop 1
	v_permlane32_swap_b32_e32 v40, v42
	v_permlane32_swap_b32_e32 v41, v43
	global_store_dwordx4 v[2:3], v[40:43], off offset:160
	v_pk_mul_f32 v[16:17], v[16:17], v[0:1] op_sel_hi:[1,0]
	v_pk_mul_f32 v[18:19], v[18:19], v[0:1] op_sel_hi:[1,0]
	v_pk_mul_f32 v[20:21], v[20:21], v[0:1] op_sel_hi:[1,0]
	v_pk_mul_f32 v[22:23], v[22:23], v[0:1] op_sel_hi:[1,0]
	v_cvt_pk_bf16_f32 v16, v16, v17
	v_cvt_pk_bf16_f32 v17, v18, v19
	v_cvt_pk_bf16_f32 v18, v20, v21
	v_cvt_pk_bf16_f32 v19, v22, v23
	s_nop 1
	v_permlane32_swap_b32_e32 v16, v18
	v_permlane32_swap_b32_e32 v17, v19
	global_store_dwordx4 v[2:3], v[16:19], off offset:192
	v_pk_mul_f32 v[24:25], v[24:25], v[0:1] op_sel_hi:[1,0]
	v_pk_mul_f32 v[26:27], v[26:27], v[0:1] op_sel_hi:[1,0]
	v_pk_mul_f32 v[28:29], v[28:29], v[0:1] op_sel_hi:[1,0]
	v_pk_mul_f32 v[30:31], v[30:31], v[0:1] op_sel_hi:[1,0]
	v_cvt_pk_bf16_f32 v24, v24, v25
	v_cvt_pk_bf16_f32 v25, v26, v27
	v_cvt_pk_bf16_f32 v26, v28, v29
	v_cvt_pk_bf16_f32 v27, v30, v31
	s_nop 1
	v_permlane32_swap_b32_e32 v24, v26
	v_permlane32_swap_b32_e32 v25, v27
	global_store_dwordx4 v[2:3], v[24:27], off offset:224
	s_or_b32 s2, s22, 1
	v_readfirstlane_b32 s3, v8
	s_ashr_i32 s10, s3, 6
	s_lshl_b32 s27, s26, 17
	s_lshl_b32 s3, s2, 8
	s_lshl_b32 s49, s10, 5
	s_lshl_b32 s53, s2, 2
	s_lshl_b32 s2, s10, 11
	s_add_i32 s46, s27, 0x24000
	s_add_i32 s49, s49, s3
	s_ashr_i32 s3, s2, 31
	s_add_u32 s4, s23, s2
	s_addc_u32 s5, s24, s3
	s_add_u32 s8, s25, s2
	v_and_b32_e32 v0, 63, v8
	s_addc_u32 s9, s50, s3
	s_add_i32 s52, s2, 0
	v_lshlrev_b32_e32 v0, 4, v0
	s_mov_b32 m0, s52
	v_lshl_add_u64 v[2:3], s[4:5], 0, v[0:1]
	global_load_lds_dwordx4 v0, s[4:5]
	s_add_i32 m0, s52, 0x400
	s_mov_b64 s[12:13], 0x400
	s_cmp_gt_i32 s10, 3
	v_lshl_add_u64 v[4:5], v[2:3], 0, s[12:13]
	s_cselect_b64 s[4:5], -1, 0
	s_cmp_lt_i32 s10, 4
	global_load_lds_dwordx4 v[4:5], off
	s_cselect_b64 s[6:7], -1, 0
	v_lshl_add_u64 v[4:5], v[2:3], 0, s[74:75]
	s_add_i32 m0, s52, 0x4000
	s_mov_b64 s[14:15], 0x4400
; __device__ __forceinline__ int pi32(int rho) { return (rho & 0x13) | ((rho & 4) << 1) | ((rho & 8) >> 1); }
; #define ATT_DMAK(t) do { const int sl_ = (t) % NSLOT; _Pragma("unroll") for (int i = 0; i < 2; ++i) \
;         __builtin_amdgcn_global_load_lds((const unsigned*)(Kg + (size_t)(t) * 16384 + i * 1024), (LAS unsigned*)(lds + OFF_K + sl_ * KBUF + wid * 2048 + i * 1024), 16, 0, 0); } while (0)
; #define ATT_DMAV(t) do { const int sl_ = (t) % NSLOT; _Pragma("unroll") for (int i = 0; i < 2; ++i) \
;         __builtin_amdgcn_global_load_lds((const unsigned*)(Vg + (size_t)(t) * 16384 + i * 1024), (LAS unsigned*)(lds + OFF_V + sl_ * VBUF + wid * 2048 + i * 1024), 16, 0, 0); } while (0)
; __device__ __forceinline__ void attn_unit(LAS unsigned char* lds, int b, int hh, int qb, const bf16_t* QK, const bf16_t* VT, bf16_t* CAT) {
;     ...
;     const char* Kg = (const char*)(QK + (size_t)(b * 32 + kch) * SEQ * HD) + wid * 2048 + lane * 16;
;     const char* Vg = (const char*)(VT + (size_t)(b * 16 + hh) * SEQ * HD) + wid * 2048 + lane * 16;
;     ...
;     ATT_DMAK(0); ATT_DMAK(1); ATT_DMAV(0);
;     bf16x8 qf[8];
;     { const bf16_t* Qp = QK + ((size_t)(b * 32 + qch) * SEQ + qpos) * HD;
; #pragma unroll
;       for (int d0 = 0; d0 < 8; ++d0) qf[d0] = *(const bf16x8*)(Qp + (((2 * d0 + hi) ^ (qpos & 15)) << 3)); }
;     const int krow = pi32(r32);
;     int koff[8];
; #pragma unroll
;     for (int d0 = 0; d0 < 8; ++d0) koff[d0] = krow * 256 + (((2 * d0 + hi) ^ (krow & 15)) << 4);
;     int voff[4];
; #pragma unroll
;     for (int c = 0; c < 4; ++c) voff[c] = r32 * 128 + (((2 * c + hi) ^ ((r32 >> 1) & 7)) << 4);
;     f32x16 o[4];
; #pragma unroll
;     for (int d = 0; d < 4; ++d)
; #pragma unroll
;         for (int i = 0; i < 16; ++i) o[d][i] = 0.f;
;     float mrun = -1e30f, lrun = 0.f;
;     f32x16 s0, s1;
;     bf16x8 pf[4];
;     bool v0 = false, v1 = false, pv0 = false, pv1 = false;
; #pragma unroll
;     for (int i = 0; i < 16; ++i) { s0[i] = 0.f; s1[i] = 0.f; }
; #pragma unroll
;     for (int i = 0; i < 4; ++i) pf[i] = (bf16x8){0, 0, 0, 0, 0, 0, 0, 0};
	v_and_b32_e32 v9, 31, v8
	global_load_lds_dwordx4 v[4:5], off
	v_lshl_add_u64 v[2:3], v[2:3], 0, s[14:15]
	s_add_i32 m0, s52, 0x4400
	v_or_b32_e32 v160, s49, v9
	global_load_lds_dwordx4 v[2:3], off
	v_lshl_add_u64 v[2:3], s[8:9], 0, v[0:1]
	s_add_i32 m0, s52, 0xc000
	v_bfe_u32 v10, v8, 5, 1
	global_load_lds_dwordx4 v0, s[8:9]
	v_lshl_add_u64 v[2:3], v[2:3], 0, s[12:13]
	s_add_i32 m0, s52, 0xc400
	v_ashrrev_i32_e32 v161, 31, v160
	global_load_lds_dwordx4 v[2:3], off
	v_lshlrev_b64 v[2:3], 8, v[160:161]
	v_and_b32_e32 v11, 15, v8
	v_bitop3_b32 v4, v10, v8, 15 bitop3:0x78
	v_lshl_add_u64 v[2:3], s[54:55], 0, v[2:3]
	v_lshlrev_b32_e32 v4, 4, v4
	v_mov_b32_e32 v5, v1
	v_bitop3_b32 v6, v10, v11, 2 bitop3:0x36
	v_lshl_add_u64 v[4:5], v[2:3], 0, v[4:5]
	v_lshlrev_b32_e32 v6, 4, v6
	v_mov_b32_e32 v7, v1
	v_lshl_add_u64 v[6:7], v[2:3], 0, v[6:7]
	global_load_dwordx4 v[112:115], v[4:5], off
	global_load_dwordx4 v[116:119], v[6:7], off
	v_bitop3_b32 v4, v10, v11, 4 bitop3:0x36
	v_lshlrev_b32_e32 v4, 4, v4
	v_mov_b32_e32 v5, v1
	v_bitop3_b32 v6, v10, v11, 6 bitop3:0x36
	v_lshl_add_u64 v[4:5], v[2:3], 0, v[4:5]
	v_lshlrev_b32_e32 v6, 4, v6
	v_mov_b32_e32 v7, v1
	v_lshl_add_u64 v[6:7], v[2:3], 0, v[6:7]
	global_load_dwordx4 v[120:123], v[4:5], off
	global_load_dwordx4 v[124:127], v[6:7], off
	v_bitop3_b32 v4, v10, v11, 8 bitop3:0x36
	v_lshlrev_b32_e32 v4, 4, v4
	v_mov_b32_e32 v5, v1
	v_bitop3_b32 v6, v10, v11, 10 bitop3:0x36
	v_lshl_add_u64 v[4:5], v[2:3], 0, v[4:5]
	v_lshlrev_b32_e32 v6, 4, v6
	v_mov_b32_e32 v7, v1
	v_lshl_add_u64 v[6:7], v[2:3], 0, v[6:7]
	global_load_dwordx4 v[128:131], v[4:5], off
	global_load_dwordx4 v[132:135], v[6:7], off
	v_bitop3_b32 v4, v10, v11, 12 bitop3:0x36
	v_lshlrev_b32_e32 v4, 4, v4
	v_mov_b32_e32 v5, v1
	v_bitop3_b32 v6, v10, v11, 14 bitop3:0x36
	v_lshl_add_u64 v[4:5], v[2:3], 0, v[4:5]
	v_lshlrev_b32_e32 v6, 4, v6
	v_mov_b32_e32 v7, v1
	v_lshl_add_u64 v[2:3], v[2:3], 0, v[6:7]
	global_load_dwordx4 v[136:139], v[4:5], off
	global_load_dwordx4 v[140:143], v[2:3], off
	v_lshlrev_b32_e32 v3, 1, v8
	v_lshrrev_b32_e32 v4, 1, v8
	v_and_b32_e32 v2, 19, v8
	v_and_b32_e32 v3, 8, v3
	v_and_b32_e32 v5, 4, v4
	v_or3_b32 v6, v5, v2, v3
	v_or_b32_e32 v12, 2, v10
	v_bitop3_b32 v7, v6, v10, 15 bitop3:0x6c
	v_or_b32_e32 v13, 4, v10
	v_lshlrev_b32_e32 v163, 4, v7
	v_bitop3_b32 v7, v6, v12, 15 bitop3:0x6c
	s_add_i32 s53, s53, 4
	v_or_b32_e32 v14, 6, v10
	v_lshlrev_b32_e32 v178, 4, v7
	v_bitop3_b32 v7, v6, v13, 15 bitop3:0x6c
	s_or_b32 s58, s49, 31
	s_or_b32 s59, s49, 1
	v_or_b32_e32 v15, 8, v10
	v_lshlrev_b32_e32 v179, 4, v7
	v_bitop3_b32 v7, v6, v14, 15 bitop3:0x6c
	s_add_u32 s8, s60, s92
	v_or_b32_e32 v16, 10, v10
	v_lshlrev_b32_e32 v180, 4, v7
	v_bitop3_b32 v7, v6, v15, 15 bitop3:0x6c
	s_addc_u32 s9, s61, s93
	v_or_b32_e32 v17, 12, v10
	v_or_b32_e32 v18, 14, v10
	v_lshlrev_b32_e32 v181, 4, v7
	v_bitop3_b32 v7, v6, v16, 15 bitop3:0x6c
	v_lshl_add_u64 v[164:165], s[8:9], 0, v[0:1]
	s_add_u32 s8, s60, s56
	v_lshlrev_b32_e32 v182, 4, v7
	v_bitop3_b32 v7, v6, v17, 15 bitop3:0x6c
	v_bitop3_b32 v6, v6, v18, 15 bitop3:0x6c
	s_addc_u32 s9, s61, s57
	v_lshlrev_b32_e32 v184, 4, v6
	v_bfe_u32 v6, v8, 1, 3
	v_bitop3_b32 v4, v10, v4, 7 bitop3:0x78
	v_and_b32_e32 v189, 32, v8
	v_lshl_add_u64 v[176:177], s[8:9], 0, v[0:1]
	v_lshlrev_b32_e32 v0, 2, v9
	v_lshlrev_b32_e32 v185, 4, v4
	v_bitop3_b32 v4, v10, v6, 2 bitop3:0x36
	v_sub_u32_e32 v0, v189, v0
	s_lshl_b32 s8, s10, 7
	v_lshlrev_b32_e32 v186, 4, v4
	v_bitop3_b32 v4, v10, v6, 4 bitop3:0x36
	v_subrev_u32_e32 v0, s8, v0
	v_lshlrev_b32_e32 v187, 4, v4
	v_bitop3_b32 v4, v10, v6, 6 bitop3:0x36
	s_waitcnt vmcnt(0) lgkmcnt(0)
	s_barrier
	v_subrev_u32_e32 v190, s1, v0
	v_or3_b32 v0, v2, v3, v5
	v_mov_b32_e32 v14, v1
	v_mov_b32_e32 v15, v1
	v_lshlrev_b32_e32 v183, 4, v7
	v_lshlrev_b32_e32 v188, 4, v4
	v_lshlrev_b32_e32 v162, 3, v10
	v_lshl_add_u32 v191, v0, 8, 0
	v_lshl_add_u32 v192, v9, 7, 0
	v_mov_b32_e32 v0, v1
	v_mov_b32_e32 v2, v1
	v_mov_b32_e32 v3, v1
	v_mov_b32_e32 v4, v1
	v_mov_b32_e32 v5, v1
	v_mov_b32_e32 v6, v1
	v_mov_b32_e32 v7, v1
	v_mov_b32_e32 v8, v1
	v_mov_b32_e32 v9, v1
	v_mov_b32_e32 v10, v1
	v_mov_b32_e32 v11, v1
	v_mov_b32_e32 v12, v1
	v_mov_b32_e32 v13, v1
	v_mov_b64_e32 v[78:79], v[14:15]
	v_mov_b64_e32 v[62:63], v[14:15]
	v_mov_b64_e32 v[46:47], v[14:15]
	v_mov_b64_e32 v[30:31], v[14:15]
	v_mov_b64_e32 v[110:111], v[14:15]
	v_mov_b64_e32 v[94:95], v[14:15]
	s_mov_b32 s48, 1
	s_mov_b32 s28, 63
	s_mov_b32 s51, 2
	v_mov_b32_e32 v161, v160
	s_mov_b32 s1, 0
	s_mov_b64 s[8:9], 0
	v_mov_b32_e32 v195, 0xf149f2ca
	v_mov_b32_e32 v194, 0
	s_mov_b32 s63, -1
	v_mov_b32_e32 v152, 0
	v_mov_b32_e32 v153, 0
	v_mov_b32_e32 v154, 0
	v_mov_b32_e32 v155, 0
	v_mov_b32_e32 v156, 0
	v_mov_b32_e32 v157, 0
	v_mov_b32_e32 v158, 0
	v_mov_b32_e32 v159, 0
	v_mov_b32_e32 v144, 0
	v_mov_b32_e32 v145, 0
	v_mov_b32_e32 v146, 0
	v_mov_b32_e32 v147, 0
	v_mov_b32_e32 v148, 0
	v_mov_b32_e32 v149, 0
	v_mov_b32_e32 v150, 0
	v_mov_b32_e32 v151, 0
	v_mov_b32_e32 v193, v189
	v_mov_b64_e32 v[76:77], v[12:13]
	v_mov_b64_e32 v[74:75], v[10:11]
	v_mov_b64_e32 v[72:73], v[8:9]
	v_mov_b64_e32 v[70:71], v[6:7]
	v_mov_b64_e32 v[68:69], v[4:5]
	v_mov_b64_e32 v[66:67], v[2:3]
	v_mov_b64_e32 v[64:65], v[0:1]
	v_mov_b64_e32 v[60:61], v[12:13]
	v_mov_b64_e32 v[58:59], v[10:11]
	v_mov_b64_e32 v[56:57], v[8:9]
	v_mov_b64_e32 v[54:55], v[6:7]
	v_mov_b64_e32 v[52:53], v[4:5]
	v_mov_b64_e32 v[50:51], v[2:3]
	v_mov_b64_e32 v[48:49], v[0:1]
	v_mov_b64_e32 v[44:45], v[12:13]
	v_mov_b64_e32 v[42:43], v[10:11]
	v_mov_b64_e32 v[40:41], v[8:9]
	v_mov_b64_e32 v[38:39], v[6:7]
	v_mov_b64_e32 v[36:37], v[4:5]
	v_mov_b64_e32 v[34:35], v[2:3]
	v_mov_b64_e32 v[32:33], v[0:1]
	v_mov_b64_e32 v[28:29], v[12:13]
	v_mov_b64_e32 v[26:27], v[10:11]
	v_mov_b64_e32 v[24:25], v[8:9]
	v_mov_b64_e32 v[22:23], v[6:7]
	v_mov_b64_e32 v[20:21], v[4:5]
	v_mov_b64_e32 v[18:19], v[2:3]
	v_mov_b64_e32 v[16:17], v[0:1]
	v_mov_b64_e32 v[108:109], v[12:13]
	v_mov_b64_e32 v[106:107], v[10:11]
	v_mov_b64_e32 v[104:105], v[8:9]
	v_mov_b64_e32 v[102:103], v[6:7]
	v_mov_b64_e32 v[100:101], v[4:5]
	v_mov_b64_e32 v[98:99], v[2:3]
	v_mov_b64_e32 v[96:97], v[0:1]
	v_mov_b64_e32 v[92:93], v[12:13]
	v_mov_b64_e32 v[90:91], v[10:11]
	v_mov_b64_e32 v[88:89], v[8:9]
	v_mov_b64_e32 v[86:87], v[6:7]
	v_mov_b64_e32 v[84:85], v[4:5]
	v_mov_b64_e32 v[82:83], v[2:3]
	v_mov_b64_e32 v[80:81], v[0:1]
	s_mov_b64 s[10:11], 0
	s_mov_b64 s[18:19], 0
	s_mov_b64 s[16:17], 0
	s_mov_b32 s66, 0
	s_waitcnt vmcnt(0)
	s_branch .LBB0_395

; #define LAS __attribute__((address_space(3)))
; __device__ __forceinline__ unsigned cvtpk(float lo, float hi) { f32x2 v = {lo, hi}; bf16x2_t b = __builtin_convertvector(v, bf16x2_t); return __builtin_bit_cast(unsigned, b); }
; __device__ __forceinline__ int opaque_tid() { int t = threadIdx.x; asm volatile("" : "+v"(t)); return t; }
; #define ATT_DMAK(t) do { const int sl_ = (t) % NSLOT; _Pragma("unroll") for (int i = 0; i < 2; ++i) \
;         __builtin_amdgcn_global_load_lds((const unsigned*)(Kg + (size_t)(t) * 16384 + i * 1024), (LAS unsigned*)(lds + OFF_K + sl_ * KBUF + wid * 2048 + i * 1024), 16, 0, 0); } while (0)
; #define ATT_DMAV(t) do { const int sl_ = (t) % NSLOT; _Pragma("unroll") for (int i = 0; i < 2; ++i) \
;         __builtin_amdgcn_global_load_lds((const unsigned*)(Vg + (size_t)(t) * 16384 + i * 1024), (LAS unsigned*)(lds + OFF_V + sl_ * VBUF + wid * 2048 + i * 1024), 16, 0, 0); } while (0)
; __device__ __forceinline__ void attn_unit(LAS unsigned char* lds, int b, int hh, int qb, const bf16_t* QK, const bf16_t* VT, bf16_t* CAT) {
;     const int tid = opaque_tid(), lane = tid & 63, r32 = lane & 31, hi = lane >> 5; const int wid = __builtin_amdgcn_readfirstlane(tid >> 6);
;     const bool fox = hh < NH;
;     const bool lead = wid < 4;
;     const int qch = fox ? hh : hh + 8, kch = qch + 8;
;     const int q0 = qb * 256 + wid * 32, qpos = q0 + r32;
;     const LAS float* tab = (const LAS float*)(lds + OFF_TAB);
;     const float C = 0.08838834764831845f * LOG2E;
;     const int nt = (qb + 1) * 4;
;     const char* Kg = (const char*)(QK + (size_t)(b * 32 + kch) * SEQ * HD) + wid * 2048 + lane * 16;
;     const char* Vg = (const char*)(VT + (size_t)(b * 16 + hh) * SEQ * HD) + wid * 2048 + lane * 16;
;     ...
;     ATT_DMAK(0); ATT_DMAK(1); ATT_DMAV(0);
;     ...
;     lrun += __shfl_xor(lrun, 32);
;     const float inv = 1.0f / lrun;
;     bf16_t* Op = CAT + (size_t)(b * SEQ + qpos) * DM + hh * HD + 4 * hi;
; #pragma unroll
;     for (int d = 0; d < 4; ++d)
; #pragma unroll
;         for (int g = 0; g < 4; ++g) { u32x2 w; w.x = cvtpk(o[d][4 * g] * inv, o[d][4 * g + 1] * inv); w.y = cvtpk(o[d][4 * g + 2] * inv, o[d][4 * g + 3] * inv);
;             *(u32x2*)(Op + 32 * d + 8 * g) = w; }
.LBB0_466:
	ds_bpermute_b32 v0, v175, v194
	v_add_u32_e32 v2, s29, v160
	v_mov_b32_e32 v163, v1
	v_mov_b32_e32 v10, v166
	s_lshl_b32 s8, s26, 9
	s_waitcnt lgkmcnt(0)
	v_add_f32_e32 v0, v194, v0
	v_div_scale_f32 v3, s[2:3], v0, v0, 1.0
	v_rcp_f32_e32 v4, v3
	v_div_scale_f32 v5, vcc, 1.0, v0, 1.0
	v_readlane_b32 s2, v250, 53
	v_fma_f32 v6, -v3, v4, 1.0
	v_fmac_f32_e32 v4, v6, v4
	v_mul_f32_e32 v6, v5, v4
	v_fma_f32 v7, -v3, v6, v5
	v_fmac_f32_e32 v6, v7, v4
	v_fma_f32 v3, -v3, v6, v5
	v_div_fmas_f32 v3, v3, v4, v6
	v_div_fixup_f32 v0, v3, v0, 1.0
	s_nop 1
	v_ashrrev_i32_e32 v3, 31, v2
	v_lshlrev_b64 v[2:3], 12, v[2:3]
	v_readlane_b32 s3, v250, 54
	v_lshl_add_u64 v[2:3], s[2:3], 0, v[2:3]
	v_lshl_add_u64 v[2:3], v[2:3], 0, s[64:65]
	v_lshl_add_u64 v[2:3], v[2:3], 0, v[162:163]
	v_lshl_add_u64 v[2:3], v[2:3], 0, v[162:163]
	v_pk_mul_f32 v[64:65], v[64:65], v[0:1] op_sel_hi:[1,0]
	v_pk_mul_f32 v[66:67], v[66:67], v[0:1] op_sel_hi:[1,0]
	v_pk_mul_f32 v[68:69], v[68:69], v[0:1] op_sel_hi:[1,0]
	v_pk_mul_f32 v[70:71], v[70:71], v[0:1] op_sel_hi:[1,0]
	v_cvt_pk_bf16_f32 v64, v64, v65
	v_cvt_pk_bf16_f32 v65, v66, v67
	v_cvt_pk_bf16_f32 v66, v68, v69
	v_cvt_pk_bf16_f32 v67, v70, v71
	s_nop 1
	v_permlane32_swap_b32_e32 v64, v66
	v_permlane32_swap_b32_e32 v65, v67
	global_store_dwordx4 v[2:3], v[64:67], off
	v_pk_mul_f32 v[72:73], v[72:73], v[0:1] op_sel_hi:[1,0]
	v_pk_mul_f32 v[74:75], v[74:75], v[0:1] op_sel_hi:[1,0]
	v_pk_mul_f32 v[76:77], v[76:77], v[0:1] op_sel_hi:[1,0]
	v_pk_mul_f32 v[78:79], v[78:79], v[0:1] op_sel_hi:[1,0]
	v_cvt_pk_bf16_f32 v72, v72, v73
	v_cvt_pk_bf16_f32 v73, v74, v75
	v_cvt_pk_bf16_f32 v74, v76, v77
	v_cvt_pk_bf16_f32 v75, v78, v79
	s_nop 1
	v_permlane32_swap_b32_e32 v72, v74
	v_permlane32_swap_b32_e32 v73, v75
	global_store_dwordx4 v[2:3], v[72:75], off offset:32
	v_pk_mul_f32 v[48:49], v[48:49], v[0:1] op_sel_hi:[1,0]
	v_pk_mul_f32 v[50:51], v[50:51], v[0:1] op_sel_hi:[1,0]
	v_pk_mul_f32 v[52:53], v[52:53], v[0:1] op_sel_hi:[1,0]
	v_pk_mul_f32 v[54:55], v[54:55], v[0:1] op_sel_hi:[1,0]
	v_cvt_pk_bf16_f32 v48, v48, v49
	v_cvt_pk_bf16_f32 v49, v50, v51
	v_cvt_pk_bf16_f32 v50, v52, v53
	v_cvt_pk_bf16_f32 v51, v54, v55
	s_nop 1
	v_permlane32_swap_b32_e32 v48, v50
	v_permlane32_swap_b32_e32 v49, v51
	global_store_dwordx4 v[2:3], v[48:51], off offset:64
	v_pk_mul_f32 v[56:57], v[56:57], v[0:1] op_sel_hi:[1,0]
	v_pk_mul_f32 v[58:59], v[58:59], v[0:1] op_sel_hi:[1,0]
	v_pk_mul_f32 v[60:61], v[60:61], v[0:1] op_sel_hi:[1,0]
	v_pk_mul_f32 v[62:63], v[62:63], v[0:1] op_sel_hi:[1,0]
	v_cvt_pk_bf16_f32 v56, v56, v57
	v_cvt_pk_bf16_f32 v57, v58, v59
	v_cvt_pk_bf16_f32 v58, v60, v61
	v_cvt_pk_bf16_f32 v59, v62, v63
	s_nop 1
	v_permlane32_swap_b32_e32 v56, v58
	v_permlane32_swap_b32_e32 v57, v59
	global_store_dwordx4 v[2:3], v[56:59], off offset:96
	v_pk_mul_f32 v[32:33], v[32:33], v[0:1] op_sel_hi:[1,0]
	v_pk_mul_f32 v[34:35], v[34:35], v[0:1] op_sel_hi:[1,0]
	v_pk_mul_f32 v[36:37], v[36:37], v[0:1] op_sel_hi:[1,0]
	v_pk_mul_f32 v[38:39], v[38:39], v[0:1] op_sel_hi:[1,0]
	v_cvt_pk_bf16_f32 v32, v32, v33
	v_cvt_pk_bf16_f32 v33, v34, v35
	v_cvt_pk_bf16_f32 v34, v36, v37
	v_cvt_pk_bf16_f32 v35, v38, v39
	s_nop 1
	v_permlane32_swap_b32_e32 v32, v34
	v_permlane32_swap_b32_e32 v33, v35
	global_store_dwordx4 v[2:3], v[32:35], off offset:128
	v_pk_mul_f32 v[40:41], v[40:41], v[0:1] op_sel_hi:[1,0]
	v_pk_mul_f32 v[42:43], v[42:43], v[0:1] op_sel_hi:[1,0]
	v_pk_mul_f32 v[44:45], v[44:45], v[0:1] op_sel_hi:[1,0]
	v_pk_mul_f32 v[46:47], v[46:47], v[0:1] op_sel_hi:[1,0]
	v_cvt_pk_bf16_f32 v40, v40, v41
	v_cvt_pk_bf16_f32 v41, v42, v43
	v_cvt_pk_bf16_f32 v42, v44, v45
	v_cvt_pk_bf16_f32 v43, v46, v47
	s_nop 1
	v_permlane32_swap_b32_e32 v40, v42
	v_permlane32_swap_b32_e32 v41, v43
	global_store_dwordx4 v[2:3], v[40:43], off offset:160
	v_pk_mul_f32 v[16:17], v[16:17], v[0:1] op_sel_hi:[1,0]
	v_pk_mul_f32 v[18:19], v[18:19], v[0:1] op_sel_hi:[1,0]
	v_pk_mul_f32 v[20:21], v[20:21], v[0:1] op_sel_hi:[1,0]
	v_pk_mul_f32 v[22:23], v[22:23], v[0:1] op_sel_hi:[1,0]
	v_cvt_pk_bf16_f32 v16, v16, v17
	v_cvt_pk_bf16_f32 v17, v18, v19
	v_cvt_pk_bf16_f32 v18, v20, v21
	v_cvt_pk_bf16_f32 v19, v22, v23
	s_nop 1
	v_permlane32_swap_b32_e32 v16, v18
	v_permlane32_swap_b32_e32 v17, v19
	global_store_dwordx4 v[2:3], v[16:19], off offset:192
	v_pk_mul_f32 v[24:25], v[24:25], v[0:1] op_sel_hi:[1,0]
	v_pk_mul_f32 v[26:27], v[26:27], v[0:1] op_sel_hi:[1,0]
	v_pk_mul_f32 v[28:29], v[28:29], v[0:1] op_sel_hi:[1,0]
	v_pk_mul_f32 v[30:31], v[30:31], v[0:1] op_sel_hi:[1,0]
	v_cvt_pk_bf16_f32 v24, v24, v25
	v_cvt_pk_bf16_f32 v25, v26, v27
	v_cvt_pk_bf16_f32 v26, v28, v29
	v_cvt_pk_bf16_f32 v27, v30, v31
	s_nop 1
	v_permlane32_swap_b32_e32 v24, v26
	v_permlane32_swap_b32_e32 v25, v27
	global_store_dwordx4 v[2:3], v[24:27], off offset:224
	s_add_i32 s27, s27, 0x14000
	v_readfirstlane_b32 s2, v10
	s_ashr_i32 s6, s2, 6
	s_lshl_b32 s2, s22, 8
	s_lshl_b32 s9, s6, 5
	s_add_i32 s28, s9, s2
	s_lshl_b32 s2, s6, 11
	s_lshl_b32 s12, s22, 2
	s_ashr_i32 s3, s2, 31
	s_add_u32 s4, s23, s2
	s_addc_u32 s5, s24, s3
	s_add_u32 s10, s25, s2
	v_and_b32_e32 v0, 63, v10
	s_addc_u32 s11, s50, s3
	s_add_i32 s22, s2, 0
	v_lshlrev_b32_e32 v2, 4, v0
	s_mov_b32 m0, s22
	v_mov_b32_e32 v3, v1
	global_load_lds_dwordx4 v2, s[4:5]
	s_add_i32 m0, s22, 0x400
	v_lshl_add_u64 v[4:5], s[4:5], 0, v[2:3]
	s_mov_b64 s[14:15], 0x400
	s_cmp_gt_i32 s6, 3
	v_lshl_add_u64 v[6:7], v[4:5], 0, s[14:15]
	s_cselect_b64 s[4:5], -1, 0
	s_cmp_lt_i32 s6, 4
	global_load_lds_dwordx4 v[6:7], off
	s_cselect_b64 s[6:7], -1, 0
	s_or_b32 s23, s12, 4
	v_lshl_add_u64 v[6:7], v[4:5], 0, s[74:75]
	s_add_i32 m0, s22, 0x4000
	s_mov_b64 s[12:13], 0x4400
; __device__ __forceinline__ int pi32(int rho) { return (rho & 0x13) | ((rho & 4) << 1) | ((rho & 8) >> 1); }
; #define ATT_DMAK(t) do { const int sl_ = (t) % NSLOT; _Pragma("unroll") for (int i = 0; i < 2; ++i) \
;         __builtin_amdgcn_global_load_lds((const unsigned*)(Kg + (size_t)(t) * 16384 + i * 1024), (LAS unsigned*)(lds + OFF_K + sl_ * KBUF + wid * 2048 + i * 1024), 16, 0, 0); } while (0)
; #define ATT_DMAV(t) do { const int sl_ = (t) % NSLOT; _Pragma("unroll") for (int i = 0; i < 2; ++i) \
;         __builtin_amdgcn_global_load_lds((const unsigned*)(Vg + (size_t)(t) * 16384 + i * 1024), (LAS unsigned*)(lds + OFF_V + sl_ * VBUF + wid * 2048 + i * 1024), 16, 0, 0); } while (0)
; __device__ __forceinline__ void attn_unit(LAS unsigned char* lds, int b, int hh, int qb, const bf16_t* QK, const bf16_t* VT, bf16_t* CAT) {
;     ...
;     const char* Kg = (const char*)(QK + (size_t)(b * 32 + kch) * SEQ * HD) + wid * 2048 + lane * 16;
;     const char* Vg = (const char*)(VT + (size_t)(b * 16 + hh) * SEQ * HD) + wid * 2048 + lane * 16;
;     ...
;     ATT_DMAK(0); ATT_DMAK(1); ATT_DMAV(0);
;     bf16x8 qf[8];
;     { const bf16_t* Qp = QK + ((size_t)(b * 32 + qch) * SEQ + qpos) * HD;
; #pragma unroll
;       for (int d0 = 0; d0 < 8; ++d0) qf[d0] = *(const bf16x8*)(Qp + (((2 * d0 + hi) ^ (qpos & 15)) << 3)); }
;     const int krow = pi32(r32);
;     int koff[8];
; #pragma unroll
;     for (int d0 = 0; d0 < 8; ++d0) koff[d0] = krow * 256 + (((2 * d0 + hi) ^ (krow & 15)) << 4);
;     int voff[4];
; #pragma unroll
;     for (int c = 0; c < 4; ++c) voff[c] = r32 * 128 + (((2 * c + hi) ^ ((r32 >> 1) & 7)) << 4);
;     f32x16 o[4];
; #pragma unroll
;     for (int d = 0; d < 4; ++d)
; #pragma unroll
;         for (int i = 0; i < 16; ++i) o[d][i] = 0.f;
;     float mrun = -1e30f, lrun = 0.f;
;     f32x16 s0, s1;
;     bf16x8 pf[4];
;     bool v0 = false, v1 = false, pv0 = false, pv1 = false;
; #pragma unroll
;     for (int i = 0; i < 16; ++i) { s0[i] = 0.f; s1[i] = 0.f; }
; #pragma unroll
;     for (int i = 0; i < 4; ++i) pf[i] = (bf16x8){0, 0, 0, 0, 0, 0, 0, 0};
	v_and_b32_e32 v11, 31, v10
	global_load_lds_dwordx4 v[6:7], off
	v_lshl_add_u64 v[4:5], v[4:5], 0, s[12:13]
	s_add_i32 m0, s22, 0x4400
	v_or_b32_e32 v146, s28, v11
	global_load_lds_dwordx4 v[4:5], off
	v_lshl_add_u64 v[4:5], s[10:11], 0, v[2:3]
	s_add_i32 m0, s22, 0xc000
	v_bfe_u32 v12, v10, 5, 1
	global_load_lds_dwordx4 v2, s[10:11]
	v_lshl_add_u64 v[4:5], v[4:5], 0, s[14:15]
	s_add_i32 m0, s22, 0xc400
	v_ashrrev_i32_e32 v147, 31, v146
	global_load_lds_dwordx4 v[4:5], off
	v_lshlrev_b64 v[4:5], 8, v[146:147]
	v_bitop3_b32 v0, v12, v10, 15 bitop3:0x78
	v_lshl_add_u64 v[4:5], s[54:55], 0, v[4:5]
	v_and_b32_e32 v13, 15, v10
	v_lshlrev_b32_e32 v0, 4, v0
	v_lshl_add_u64 v[6:7], v[4:5], 0, v[0:1]
	v_bitop3_b32 v0, v12, v13, 2 bitop3:0x36
	v_lshlrev_b32_e32 v0, 4, v0
	v_lshl_add_u64 v[8:9], v[4:5], 0, v[0:1]
	v_bitop3_b32 v0, v12, v13, 4 bitop3:0x36
	v_lshlrev_b32_e32 v0, 4, v0
	global_load_dwordx4 v[98:101], v[6:7], off
	global_load_dwordx4 v[102:105], v[8:9], off
	v_lshl_add_u64 v[6:7], v[4:5], 0, v[0:1]
	v_bitop3_b32 v0, v12, v13, 6 bitop3:0x36
	v_lshlrev_b32_e32 v0, 4, v0
	v_lshl_add_u64 v[8:9], v[4:5], 0, v[0:1]
	v_bitop3_b32 v0, v12, v13, 8 bitop3:0x36
	v_lshlrev_b32_e32 v0, 4, v0
	global_load_dwordx4 v[106:109], v[6:7], off
	global_load_dwordx4 v[110:113], v[8:9], off
	v_lshl_add_u64 v[6:7], v[4:5], 0, v[0:1]
	v_bitop3_b32 v0, v12, v13, 10 bitop3:0x36
	v_lshlrev_b32_e32 v0, 4, v0
	v_lshl_add_u64 v[8:9], v[4:5], 0, v[0:1]
	v_bitop3_b32 v0, v12, v13, 12 bitop3:0x36
	v_lshlrev_b32_e32 v0, 4, v0
	global_load_dwordx4 v[114:117], v[6:7], off
	global_load_dwordx4 v[118:121], v[8:9], off
	v_lshl_add_u64 v[6:7], v[4:5], 0, v[0:1]
	v_bitop3_b32 v0, v12, v13, 14 bitop3:0x36
	v_lshlrev_b32_e32 v0, 4, v0
	v_lshl_add_u64 v[4:5], v[4:5], 0, v[0:1]
	global_load_dwordx4 v[122:125], v[6:7], off
	global_load_dwordx4 v[126:129], v[4:5], off
	v_lshlrev_b32_e32 v0, 1, v10
	v_and_b32_e32 v5, 8, v0
	v_lshrrev_b32_e32 v0, 1, v10
	v_and_b32_e32 v4, 19, v10
	v_and_b32_e32 v6, 4, v0
	v_or3_b32 v7, v6, v4, v5
	v_or_b32_e32 v14, 2, v12
	v_bitop3_b32 v13, v7, v12, 15 bitop3:0x6c
	v_or_b32_e32 v15, 4, v12
	v_lshlrev_b32_e32 v160, 4, v13
	v_bitop3_b32 v13, v7, v14, 15 bitop3:0x6c
	v_or_b32_e32 v16, 6, v12
	v_lshlrev_b32_e32 v161, 4, v13
	v_bitop3_b32 v13, v7, v15, 15 bitop3:0x6c
	s_or_b32 s24, s28, 31
	s_or_b32 s25, s28, 1
	v_or_b32_e32 v17, 8, v12
	v_lshlrev_b32_e32 v162, 4, v13
	v_bitop3_b32 v13, v7, v16, 15 bitop3:0x6c
	s_add_u32 s10, s60, s92
	v_or_b32_e32 v18, 10, v12
	v_or_b32_e32 v8, 12, v12
	v_or_b32_e32 v9, 14, v12
	v_lshlrev_b32_e32 v163, 4, v13
	v_bitop3_b32 v13, v7, v17, 15 bitop3:0x6c
	s_addc_u32 s11, s61, s93
	v_lshlrev_b32_e32 v164, 4, v13
	v_bitop3_b32 v13, v7, v18, 15 bitop3:0x6c
	v_bitop3_b32 v8, v7, v8, 15 bitop3:0x6c
	v_bitop3_b32 v7, v7, v9, 15 bitop3:0x6c
	v_lshl_add_u64 v[148:149], s[10:11], 0, v[2:3]
	s_add_u32 s10, s60, s56
	v_lshlrev_b32_e32 v177, 4, v7
	v_bfe_u32 v7, v10, 1, 3
	v_bitop3_b32 v0, v12, v0, 7 bitop3:0x78
	s_addc_u32 s11, s61, s57
	s_add_i32 s8, s8, s9
	v_lshlrev_b32_e32 v178, 4, v0
	v_bitop3_b32 v0, v12, v7, 2 bitop3:0x36
	v_lshl_add_u64 v[150:151], s[10:11], 0, v[2:3]
	v_or_b32_e32 v2, s8, v11
	v_lshlrev_b32_e32 v179, 4, v0
	v_bitop3_b32 v0, v12, v7, 4 bitop3:0x36
	v_and_b32_e32 v182, 32, v10
	v_lshlrev_b32_e32 v2, 2, v2
	v_lshlrev_b32_e32 v180, 4, v0
	v_bitop3_b32 v0, v12, v7, 6 bitop3:0x36
	s_waitcnt vmcnt(0) lgkmcnt(0)
	s_barrier
	v_sub_u32_e32 v183, v182, v2
	v_or3_b32 v2, v4, v5, v6
	v_mov_b32_e32 v34, v1
	v_mov_b32_e32 v35, v1
	v_mov_b32_e32 v48, v1
	v_mov_b32_e32 v49, v1
	v_lshlrev_b32_e32 v165, 4, v13
	v_lshlrev_b32_e32 v176, 4, v8
	v_lshlrev_b32_e32 v181, 4, v0
	v_lshlrev_b32_e32 v0, 3, v12
	v_lshl_add_u32 v184, v2, 8, 0
	v_lshl_add_u32 v185, v11, 7, 0
	v_mov_b32_e32 v36, v1
	v_mov_b32_e32 v37, v1
	v_mov_b32_e32 v38, v1
	v_mov_b32_e32 v39, v1
	v_mov_b32_e32 v40, v1
	v_mov_b32_e32 v41, v1
	v_mov_b32_e32 v42, v1
	v_mov_b32_e32 v43, v1
	v_mov_b32_e32 v44, v1
	v_mov_b32_e32 v45, v1
	v_mov_b32_e32 v46, v1
	v_mov_b32_e32 v47, v1
	v_mov_b64_e32 v[64:65], v[48:49]
	v_mov_b64_e32 v[18:19], v[34:35]
	v_mov_b64_e32 v[2:3], v[34:35]
	v_mov_b64_e32 v[96:97], v[48:49]
	v_mov_b64_e32 v[80:81], v[48:49]
	s_mov_b32 s1, 1
	s_mov_b32 s26, 63
	s_mov_b32 s46, 2
	v_mov_b32_e32 v147, v146
	s_mov_b32 s48, 0
	s_mov_b64 s[8:9], 0
	v_mov_b32_e32 v188, 0xf149f2ca
	v_mov_b32_e32 v187, 0
	s_mov_b32 s49, -1
	v_mov_b32_e32 v138, 0
	v_mov_b32_e32 v139, 0
	v_mov_b32_e32 v140, 0
	v_mov_b32_e32 v141, 0
	v_mov_b32_e32 v142, 0
	v_mov_b32_e32 v143, 0
	v_mov_b32_e32 v144, 0
	v_mov_b32_e32 v145, 0
	v_mov_b32_e32 v130, 0
	v_mov_b32_e32 v131, 0
	v_mov_b32_e32 v132, 0
	v_mov_b32_e32 v133, 0
	v_mov_b32_e32 v134, 0
	v_mov_b32_e32 v135, 0
	v_mov_b32_e32 v136, 0
	v_mov_b32_e32 v137, 0
	v_mov_b32_e32 v186, v182
	v_mov_b64_e32 v[62:63], v[46:47]
	v_mov_b64_e32 v[60:61], v[44:45]
	v_mov_b64_e32 v[58:59], v[42:43]
	v_mov_b64_e32 v[56:57], v[40:41]
	v_mov_b64_e32 v[54:55], v[38:39]
	v_mov_b64_e32 v[52:53], v[36:37]
	v_mov_b64_e32 v[50:51], v[34:35]
	v_mov_b64_e32 v[20:21], v[36:37]
	v_mov_b64_e32 v[22:23], v[38:39]
	v_mov_b64_e32 v[24:25], v[40:41]
	v_mov_b64_e32 v[26:27], v[42:43]
	v_mov_b64_e32 v[28:29], v[44:45]
	v_mov_b64_e32 v[30:31], v[46:47]
	v_mov_b64_e32 v[32:33], v[48:49]
	v_mov_b64_e32 v[4:5], v[36:37]
	v_mov_b64_e32 v[6:7], v[38:39]
	v_mov_b64_e32 v[8:9], v[40:41]
	v_mov_b64_e32 v[10:11], v[42:43]
	v_mov_b64_e32 v[12:13], v[44:45]
	v_mov_b64_e32 v[14:15], v[46:47]
	v_mov_b64_e32 v[16:17], v[48:49]
	v_mov_b64_e32 v[94:95], v[46:47]
	v_mov_b64_e32 v[92:93], v[44:45]
	v_mov_b64_e32 v[90:91], v[42:43]
	v_mov_b64_e32 v[88:89], v[40:41]
	v_mov_b64_e32 v[86:87], v[38:39]
	v_mov_b64_e32 v[84:85], v[36:37]
	v_mov_b64_e32 v[82:83], v[34:35]
	v_mov_b64_e32 v[78:79], v[46:47]
	v_mov_b64_e32 v[76:77], v[44:45]
	v_mov_b64_e32 v[74:75], v[42:43]
	v_mov_b64_e32 v[72:73], v[40:41]
	v_mov_b64_e32 v[70:71], v[38:39]
	v_mov_b64_e32 v[68:69], v[36:37]
	v_mov_b64_e32 v[66:67], v[34:35]
	s_mov_b64 s[10:11], 0
	s_mov_b64 s[18:19], 0
	s_mov_b64 s[16:17], 0
	s_mov_b32 s50, 0
	s_waitcnt vmcnt(0)
	s_branch .LBB0_468
